# XA-step converter f32 weight loads with nt hint (keep streaming traffic from evicting the concurrent q-GEMM's tiles in L2), on v58
# speedup vs baseline: 1.0016x; 1.0016x over previous
; __device__ __forceinline__ void tr_load(const float* src, int N, f32x4 (&v)[16], int lane) {
;     const int r4 = lane >> 4, c4 = (lane & 15) * 4;
; #pragma unroll
;     for (int i = 0; i < 16; ++i) v[i] = *(const f32x4*)(src + (size_t)(4 * i + r4) * N + c4);
; }
; __device__ __forceinline__ void convert_segments(const Args& args, unsigned char* ws, LAS unsigned char* lds, int seg_lo, int seg_hi, int part_lo, int part_hi, int nparts, int wid, int nw, int wave, int lane) {
;     ...
;     for (int sI = seg_lo; sI < seg_hi; ++sI) {
;         const Seg sg = seg_at(sI);
;         const int nblk = sg.ncols / 64, nit = (sg.K / 64) * nblk;
;         const float* W = args.in[sg.in_idx] + (size_t)sg.src_l * sg.K * sg.N;
;         bf16* WT = (bf16*)(ws + WS_W + (size_t)sg.layer * LAYER_W + (size_t)sg.wsub_mib * MiB);
;         const int it_lo = (int)((long)nit * part_lo / nparts), it_hi = (int)((long)nit * part_hi / nparts);
;         int it = it_lo + wid;
;         f32x4 v[16];
;         if (it < it_hi) { const int kb = it / nblk, nb = it - kb * nblk; tr_load(W + (size_t)(64 * kb) * sg.N + sg.scol + 64 * nb, sg.N, v, lane); }
.LBB0_907:
	s_mul_i32 s7, s25, 40
	s_getpc_b64 s[4:5]
	s_add_u32 s4, s4, __const._Z6seg_ati.segs@rel32@lo+4
	s_addc_u32 s5, s5, __const._Z6seg_ati.segs@rel32@hi+12
	s_mul_hi_u32 s6, s25, 40
	s_add_u32 s14, s4, s7
	s_addc_u32 s15, s5, s6
	s_load_dwordx8 s[4:11], s[14:15], 0x0
	v_lshlrev_b32_e32 v116, 2, v66
	s_waitcnt lgkmcnt(0)
	s_ashr_i32 s12, s9, 31
	s_ashr_i32 s39, s7, 31
	s_lshr_b32 s12, s12, 26
	s_lshr_b32 s26, s39, 26
	s_add_i32 s9, s9, s12
	s_ashr_i32 s44, s9, 6
	s_add_i32 s9, s7, s26
	s_ashr_i32 s27, s4, 31
	s_mov_b32 s26, s4
	s_ashr_i32 s9, s9, 6
	s_lshl_b64 s[26:27], s[26:27], 3
	s_add_u32 s26, s0, s26
	s_addc_u32 s27, s1, s27
	s_load_dwordx2 s[42:43], s[26:27], 0x0
	s_mul_i32 s12, s6, s5
	s_mul_hi_i32 s4, s6, s5
	s_mul_i32 s5, s12, s39
	s_mul_hi_u32 s27, s12, s7
	s_add_i32 s5, s27, s5
	s_mul_i32 s4, s4, s7
	s_add_i32 s5, s5, s4
	s_mul_i32 s4, s12, s7
	s_lshl_b64 s[4:5], s[4:5], 2
	s_mul_i32 s9, s44, s9
	s_waitcnt lgkmcnt(0)
	s_add_u32 s27, s42, s4
	s_addc_u32 s39, s43, s5
	s_lshr_b32 s4, s9, 31
	s_add_i32 s9, s9, s4
	s_mov_b32 s26, s7
	s_ashr_i32 s7, s9, 1
	s_cmp_lt_i32 s18, s7
	s_cselect_b64 s[4:5], -1, 0
	s_cmp_ge_i32 s18, s7
	s_cbranch_scc1 .LBB0_909
	s_abs_i32 s9, s44
	s_waitcnt vmcnt(0)
	v_cvt_f32_u32_e32 v0, s9
	s_sub_i32 s41, 0, s9
	s_ashr_i32 s12, s44, 31
	s_xor_b32 s12, s21, s12
	v_rcp_iflag_f32_e32 v0, v0
	v_mov_b32_e32 v117, v69
	v_mul_f32_e32 v0, 0x4f7ffffe, v0
	v_cvt_u32_f32_e32 v0, v0
	s_nop 0
	v_readfirstlane_b32 s42, v0
	s_mul_i32 s41, s41, s42
	s_mul_hi_u32 s41, s42, s41
	s_add_i32 s42, s42, s41
	s_mul_hi_u32 s41, s22, s42
	s_mul_i32 s42, s41, s9
	s_sub_i32 s42, s22, s42
	s_add_i32 s43, s41, 1
	s_sub_i32 s45, s42, s9
	s_cmp_ge_u32 s42, s9
	s_cselect_b32 s41, s43, s41
	s_cselect_b32 s42, s45, s42
	s_add_i32 s43, s41, 1
	s_cmp_ge_u32 s42, s9
	s_cselect_b32 s9, s43, s41
	s_xor_b32 s9, s9, s12
	s_sub_i32 s9, s9, s12
	s_mul_i32 s12, s9, s44
	s_lshl_b32 s9, s9, 6
	s_mul_hi_i32 s43, s9, s6
	s_mul_i32 s42, s9, s6
	s_sub_i32 s12, s18, s12
	s_lshl_b64 s[42:43], s[42:43], 2
	s_add_u32 s41, s27, s42
	s_addc_u32 s45, s39, s43
	s_ashr_i32 s9, s8, 31
	s_lshl_b64 s[42:43], s[8:9], 2
	s_add_u32 s9, s41, s42
	s_addc_u32 s41, s45, s43
	s_lshl_b32 s42, s12, 6
	s_ashr_i32 s43, s42, 31
	s_lshl_b64 s[42:43], s[42:43], 2
	s_add_u32 s42, s9, s42
	s_addc_u32 s43, s41, s43
	v_lshl_add_u64 v[56:57], s[42:43], 0, v[116:117]
	v_mad_i64_i32 v[0:1], s[42:43], s6, v64, 0
	v_lshl_add_u64 v[8:9], v[0:1], 2, v[56:57]
	v_mad_i64_i32 v[0:1], s[42:43], s6, v70, 0
	v_lshl_add_u64 v[10:11], v[0:1], 2, v[56:57]
	global_load_dwordx4 v[0:3], v[8:9], off nt
	global_load_dwordx4 v[4:7], v[10:11], off nt
	v_mad_i64_i32 v[8:9], s[42:43], s6, v72, 0
	v_lshl_add_u64 v[16:17], v[8:9], 2, v[56:57]
	v_mad_i64_i32 v[8:9], s[42:43], s6, v74, 0
	v_lshl_add_u64 v[18:19], v[8:9], 2, v[56:57]
	global_load_dwordx4 v[8:11], v[16:17], off nt
	global_load_dwordx4 v[12:15], v[18:19], off nt
	v_mad_i64_i32 v[16:17], s[42:43], s6, v76, 0
	v_lshl_add_u64 v[24:25], v[16:17], 2, v[56:57]
	v_mad_i64_i32 v[16:17], s[42:43], s6, v78, 0
	v_lshl_add_u64 v[26:27], v[16:17], 2, v[56:57]
	global_load_dwordx4 v[16:19], v[24:25], off nt
	global_load_dwordx4 v[20:23], v[26:27], off nt
	v_mad_i64_i32 v[24:25], s[42:43], s6, v80, 0
	v_lshl_add_u64 v[32:33], v[24:25], 2, v[56:57]
	v_mad_i64_i32 v[24:25], s[42:43], s6, v82, 0
	v_lshl_add_u64 v[34:35], v[24:25], 2, v[56:57]
	global_load_dwordx4 v[24:27], v[32:33], off nt
	global_load_dwordx4 v[28:31], v[34:35], off nt
	v_mad_i64_i32 v[32:33], s[42:43], s6, v84, 0
	v_lshl_add_u64 v[40:41], v[32:33], 2, v[56:57]
	v_mad_i64_i32 v[32:33], s[42:43], s6, v86, 0
	v_lshl_add_u64 v[42:43], v[32:33], 2, v[56:57]
	global_load_dwordx4 v[32:35], v[40:41], off nt
	global_load_dwordx4 v[36:39], v[42:43], off nt
	v_mad_i64_i32 v[40:41], s[42:43], s6, v88, 0
	v_lshl_add_u64 v[48:49], v[40:41], 2, v[56:57]
	v_mad_i64_i32 v[40:41], s[42:43], s6, v90, 0
	v_lshl_add_u64 v[50:51], v[40:41], 2, v[56:57]
	global_load_dwordx4 v[40:43], v[48:49], off nt
	global_load_dwordx4 v[44:47], v[50:51], off nt
	v_mad_i64_i32 v[48:49], s[42:43], s6, v92, 0
	v_lshl_add_u64 v[58:59], v[48:49], 2, v[56:57]
	v_mad_i64_i32 v[48:49], s[42:43], s6, v94, 0
	v_lshl_add_u64 v[60:61], v[48:49], 2, v[56:57]
	global_load_dwordx4 v[48:51], v[58:59], off nt
	global_load_dwordx4 v[52:55], v[60:61], off nt
	v_mad_i64_i32 v[58:59], s[42:43], s6, v96, 0
	v_lshl_add_u64 v[118:119], v[58:59], 2, v[56:57]
	v_mad_i64_i32 v[58:59], s[42:43], s6, v98, 0
	v_lshl_add_u64 v[120:121], v[58:59], 2, v[56:57]
	global_load_dwordx4 v[56:59], v[118:119], off nt
	global_load_dwordx4 v[60:63], v[120:121], off nt

; #define LAS __attribute__((address_space(3)))
; #define LDS_WAIT() asm volatile("s_waitcnt lgkmcnt(0)" ::: "memory")
; __device__ __forceinline__ void tr_to_lds(const f32x4 (&v)[16], LAS float* scr, int lane) {
;     const int r4 = lane >> 4, c4 = (lane & 15) * 4;
; #pragma unroll
;     for (int i = 0; i < 16; ++i) { LAS float* s = scr + (4 * i + r4) * 65 + c4; s[0] = v[i].x; s[1] = v[i].y; s[2] = v[i].z; s[3] = v[i].w; }
;     LDS_WAIT(); asm volatile("" ::: "memory");
; }
; __device__ __forceinline__ void convert_segments(const Args& args, unsigned char* ws, LAS unsigned char* lds, int seg_lo, int seg_hi, int part_lo, int part_hi, int nparts, int wid, int nw, int wave, int lane) {
;     ...
;         for (; it < it_hi; it += nw) {
;             const int kb = it / nblk, nb = it - kb * nblk;
;             const int drow = sg.ilv ? (256 * (nb >> 1) + 64 * (nb & 1) + sg.drow) : (sg.drow + 64 * nb);
;             tr_to_lds(v, scr, lane);
;             const int itn = it + nw;
;             if (itn < it_hi) { const int kbn = itn / nblk, nbn = itn - kbn * nblk; tr_load(W + (size_t)(64 * kbn) * sg.N + sg.scol + 64 * nbn, sg.N, v, lane); }
.LBB0_914:
	v_add_u32_e32 v71, 0x410, v67
	s_waitcnt vmcnt(0)
	ds_write2_b32 v67, v0, v1 offset1:1
	ds_write2_b32 v67, v2, v3 offset0:2 offset1:3
	ds_write2_b32 v71, v4, v5 offset1:1
	v_add_u32_e32 v71, 0x418, v67
	ds_write2_b32 v71, v6, v7 offset1:1
	v_add_u32_e32 v71, 0x820, v67
	ds_write2_b32 v71, v8, v9 offset1:1
	v_add_u32_e32 v71, 0x828, v67
	ds_write2_b32 v71, v10, v11 offset1:1
	v_add_u32_e32 v71, 0xc30, v67
	ds_write2_b32 v71, v12, v13 offset1:1
	v_add_u32_e32 v71, 0xc38, v67
	ds_write2_b32 v71, v14, v15 offset1:1
	v_add_u32_e32 v71, 0x1040, v67
	ds_write2_b32 v71, v16, v17 offset1:1
	v_add_u32_e32 v71, 0x1048, v67
	ds_write2_b32 v71, v18, v19 offset1:1
	v_add_u32_e32 v71, 0x1450, v67
	ds_write2_b32 v71, v20, v21 offset1:1
	v_add_u32_e32 v71, 0x1458, v67
	ds_write2_b32 v71, v22, v23 offset1:1
	v_add_u32_e32 v71, 0x1860, v67
	ds_write2_b32 v71, v24, v25 offset1:1
	v_add_u32_e32 v71, 0x1868, v67
	ds_write2_b32 v71, v26, v27 offset1:1
	v_add_u32_e32 v71, 0x1c70, v67
	ds_write2_b32 v71, v28, v29 offset1:1
	v_add_u32_e32 v71, 0x1c78, v67
	ds_write2_b32 v71, v30, v31 offset1:1
	v_add_u32_e32 v71, 0x2080, v67
	ds_write2_b32 v71, v32, v33 offset1:1
	v_add_u32_e32 v71, 0x2088, v67
	ds_write2_b32 v71, v34, v35 offset1:1
	v_add_u32_e32 v71, 0x2490, v67
	ds_write2_b32 v71, v36, v37 offset1:1
	v_add_u32_e32 v71, 0x2498, v67
	ds_write2_b32 v71, v38, v39 offset1:1
	v_add_u32_e32 v71, 0x28a0, v67
	ds_write2_b32 v71, v40, v41 offset1:1
	v_add_u32_e32 v71, 0x28a8, v67
	ds_write2_b32 v71, v42, v43 offset1:1
	v_add_u32_e32 v71, 0x2cb0, v67
	ds_write2_b32 v71, v44, v45 offset1:1
	v_add_u32_e32 v71, 0x2cb8, v67
	ds_write2_b32 v71, v46, v47 offset1:1
	v_add_u32_e32 v71, 0x30c0, v67
	ds_write2_b32 v71, v48, v49 offset1:1
	v_add_u32_e32 v71, 0x30c8, v67
	ds_write2_b32 v71, v50, v51 offset1:1
	v_add_u32_e32 v71, 0x34d0, v67
	ds_write2_b32 v71, v52, v53 offset1:1
	v_add_u32_e32 v71, 0x34d8, v67
	ds_write2_b32 v71, v54, v55 offset1:1
	v_add_u32_e32 v71, 0x38e0, v67
	ds_write2_b32 v71, v56, v57 offset1:1
	v_add_u32_e32 v71, 0x38e8, v67
	ds_write2_b32 v71, v58, v59 offset1:1
	v_add_u32_e32 v71, 0x3cf0, v67
	ds_write2_b32 v71, v60, v61 offset1:1
	v_add_u32_e32 v71, 0x3cf8, v67
	ds_write2_b32 v71, v62, v63 offset1:1
	s_waitcnt lgkmcnt(0)
	s_add_i32 s47, s50, 0x3c0
	s_cmp_ge_i32 s47, s7
	s_cselect_b64 s[8:9], -1, 0
	s_and_b64 vcc, exec, s[8:9]
	s_cbranch_vccnz .LBB0_916
	s_ashr_i32 s51, s47, 31
	s_add_i32 s50, s50, s51
	s_addk_i32 s50, 0x3c0
	s_xor_b32 s50, s50, s51
	s_xor_b32 s52, s51, s39
	s_mul_hi_u32 s51, s50, s41
	s_mul_i32 s53, s51, s27
	s_sub_i32 s50, s50, s53
	s_add_i32 s53, s51, 1
	s_sub_i32 s54, s50, s27
	s_cmp_ge_u32 s50, s27
	s_cselect_b32 s51, s53, s51
	s_cselect_b32 s50, s54, s50
	s_add_i32 s53, s51, 1
	s_cmp_ge_u32 s50, s27
	s_cselect_b32 s50, s53, s51
	s_xor_b32 s50, s50, s52
	s_sub_i32 s52, s50, s52
	s_lshl_b32 s50, s52, 6
	s_mul_hi_i32 s51, s50, s6
	s_mul_i32 s50, s50, s6
	s_lshl_b64 s[50:51], s[50:51], 2
	s_add_u32 s53, s12, s50
	s_mul_i32 s50, s42, s52
	s_addc_u32 s54, s15, s51
	s_add_i32 s50, s46, s50
	s_addk_i32 s50, 0xe000
	s_ashr_i32 s51, s50, 31
	s_lshl_b64 s[50:51], s[50:51], 2
	s_add_u32 s50, s53, s50
	s_addc_u32 s51, s54, s51
	v_mov_b32_e32 v117, v69
	v_lshl_add_u64 v[56:57], s[50:51], 0, v[116:117]
	v_lshl_add_u64 v[0:1], v[118:119], 2, v[56:57]
	v_lshl_add_u64 v[4:5], v[120:121], 2, v[56:57]
	v_lshl_add_u64 v[8:9], v[122:123], 2, v[56:57]
	v_lshl_add_u64 v[12:13], v[124:125], 2, v[56:57]
	v_lshl_add_u64 v[16:17], v[126:127], 2, v[56:57]
	v_lshl_add_u64 v[20:21], v[128:129], 2, v[56:57]
	v_lshl_add_u64 v[24:25], v[130:131], 2, v[56:57]
	v_lshl_add_u64 v[28:29], v[132:133], 2, v[56:57]
	v_lshl_add_u64 v[32:33], v[134:135], 2, v[56:57]
	v_lshl_add_u64 v[36:37], v[136:137], 2, v[56:57]
	v_lshl_add_u64 v[40:41], v[138:139], 2, v[56:57]
	v_lshl_add_u64 v[44:45], v[140:141], 2, v[56:57]
	v_lshl_add_u64 v[48:49], v[142:143], 2, v[56:57]
	v_lshl_add_u64 v[52:53], v[144:145], 2, v[56:57]
	v_lshl_add_u64 v[58:59], v[146:147], 2, v[56:57]
	v_lshl_add_u64 v[60:61], v[148:149], 2, v[56:57]
	global_load_dwordx4 v[0:3], v[0:1], off nt
	s_nop 0
	global_load_dwordx4 v[4:7], v[4:5], off nt
	s_nop 0
	global_load_dwordx4 v[8:11], v[8:9], off nt
	s_nop 0
	global_load_dwordx4 v[12:15], v[12:13], off nt
	s_nop 0
	global_load_dwordx4 v[16:19], v[16:17], off nt
	s_nop 0
	global_load_dwordx4 v[20:23], v[20:21], off nt
	s_nop 0
	global_load_dwordx4 v[24:27], v[24:25], off nt
	s_nop 0
	global_load_dwordx4 v[28:31], v[28:29], off nt
	s_nop 0
	global_load_dwordx4 v[32:35], v[32:33], off nt
	s_nop 0
	global_load_dwordx4 v[36:39], v[36:37], off nt
	s_nop 0
	global_load_dwordx4 v[40:43], v[40:41], off nt
	s_nop 0
	global_load_dwordx4 v[44:47], v[44:45], off nt
	s_nop 0
	global_load_dwordx4 v[48:51], v[48:49], off nt
	s_nop 0
	global_load_dwordx4 v[52:55], v[52:53], off nt
	s_nop 0
	global_load_dwordx4 v[56:59], v[58:59], off nt
	s_nop 0
	global_load_dwordx4 v[60:63], v[60:61], off nt

; __device__ __forceinline__ void tr_load(const float* src, int N, f32x4 (&v)[16], int lane) {
;     const int r4 = lane >> 4, c4 = (lane & 15) * 4;
; #pragma unroll
;     for (int i = 0; i < 16; ++i) v[i] = *(const f32x4*)(src + (size_t)(4 * i + r4) * N + c4);
; }
; __device__ __forceinline__ void convert_segments(const Args& args, unsigned char* ws, LAS unsigned char* lds, int seg_lo, int seg_hi, int part_lo, int part_hi, int nparts, int wid, int nw, int wave, int lane) {
;     ...
;     for (int sI = seg_lo; sI < seg_hi; ++sI) {
;         const Seg sg = seg_at(sI);
;         const int nblk = sg.ncols / 64, nit = (sg.K / 64) * nblk;
;         const float* W = args.in[sg.in_idx] + (size_t)sg.src_l * sg.K * sg.N;
;         bf16* WT = (bf16*)(ws + WS_W + (size_t)sg.layer * LAYER_W + (size_t)sg.wsub_mib * MiB);
;         const int it_lo = (int)((long)nit * part_lo / nparts), it_hi = (int)((long)nit * part_hi / nparts);
;         int it = it_lo + wid;
;         f32x4 v[16];
;         if (it < it_hi) { const int kb = it / nblk, nb = it - kb * nblk; tr_load(W + (size_t)(64 * kb) * sg.N + sg.scol + 64 * nb, sg.N, v, lane); }
.LBB0_2119:
	s_mul_i32 s7, s23, 40
	s_getpc_b64 s[4:5]
	s_add_u32 s4, s4, __const._Z6seg_ati.segs@rel32@lo+4
	s_addc_u32 s5, s5, __const._Z6seg_ati.segs@rel32@hi+12
	s_mul_hi_u32 s6, s23, 40
	s_add_u32 s14, s4, s7
	s_addc_u32 s15, s5, s6
	s_load_dwordx8 s[4:11], s[14:15], 0x0
	v_lshlrev_b32_e32 v116, 2, v66
	s_waitcnt lgkmcnt(0)
	s_ashr_i32 s12, s9, 31
	s_ashr_i32 s39, s7, 31
	s_lshr_b32 s12, s12, 26
	s_lshr_b32 s24, s39, 26
	s_add_i32 s9, s9, s12
	s_ashr_i32 s44, s9, 6
	s_add_i32 s9, s7, s24
	s_ashr_i32 s27, s4, 31
	s_mov_b32 s26, s4
	s_ashr_i32 s9, s9, 6
	s_lshl_b64 s[26:27], s[26:27], 3
	s_add_u32 s26, s0, s26
	s_addc_u32 s27, s1, s27
	s_mul_i32 s24, s44, s9
	s_load_dwordx2 s[42:43], s[26:27], 0x0
	s_mul_i32 s9, s6, s5
	s_mul_hi_i32 s4, s6, s5
	s_mul_i32 s5, s9, s39
	s_mul_hi_u32 s12, s9, s7
	s_add_i32 s5, s12, s5
	s_mul_i32 s4, s4, s7
	s_add_i32 s5, s5, s4
	s_mul_i32 s4, s9, s7
	s_lshl_b64 s[4:5], s[4:5], 2
	s_waitcnt lgkmcnt(0)
	s_add_u32 s27, s42, s4
	s_addc_u32 s39, s43, s5
	s_lshr_b32 s4, s24, 31
	s_add_i32 s4, s24, s4
	s_ashr_i32 s43, s4, 1
	s_add_i32 s26, s18, s43
	s_cmp_lt_i32 s26, s24
	s_mov_b32 s25, s7
	s_cselect_b64 s[4:5], -1, 0
	s_cmp_ge_i32 s26, s24
	s_cbranch_scc1 .LBB0_2121
	s_abs_i32 s7, s44
	s_waitcnt vmcnt(0)
	v_cvt_f32_u32_e32 v0, s7
	s_sub_i32 s41, 0, s7
	s_abs_i32 s12, s26
	s_xor_b32 s9, s26, s44
	v_rcp_iflag_f32_e32 v0, v0
	s_ashr_i32 s9, s9, 31
	v_mov_b32_e32 v117, v69
	v_mul_f32_e32 v0, 0x4f7ffffe, v0
	v_cvt_u32_f32_e32 v0, v0
	s_nop 0
	v_readfirstlane_b32 s42, v0
	s_mul_i32 s41, s41, s42
	s_mul_hi_u32 s41, s42, s41
	s_add_i32 s42, s42, s41
	s_mul_hi_u32 s41, s12, s42
	s_mul_i32 s42, s41, s7
	s_sub_i32 s12, s12, s42
	s_add_i32 s45, s41, 1
	s_sub_i32 s42, s12, s7
	s_cmp_ge_u32 s12, s7
	s_cselect_b32 s41, s45, s41
	s_cselect_b32 s12, s42, s12
	s_add_i32 s42, s41, 1
	s_cmp_ge_u32 s12, s7
	s_cselect_b32 s7, s42, s41
	s_xor_b32 s7, s7, s9
	s_sub_i32 s7, s7, s9
	s_mul_i32 s9, s7, s44
	s_lshl_b32 s7, s7, 6
	s_mul_hi_i32 s47, s7, s6
	s_mul_i32 s46, s7, s6
	s_sub_i32 s12, s26, s9
	s_lshl_b64 s[46:47], s[46:47], 2
	s_add_u32 s7, s27, s46
	s_addc_u32 s41, s39, s47
	s_ashr_i32 s9, s8, 31
	s_lshl_b64 s[46:47], s[8:9], 2
	s_add_u32 s7, s7, s46
	s_addc_u32 s9, s41, s47
	s_lshl_b32 s46, s12, 6
	s_ashr_i32 s47, s46, 31
	s_lshl_b64 s[46:47], s[46:47], 2
	s_add_u32 s46, s7, s46
	s_addc_u32 s47, s9, s47
	v_lshl_add_u64 v[56:57], s[46:47], 0, v[116:117]
	v_mad_i64_i32 v[0:1], s[46:47], s6, v64, 0
	v_lshl_add_u64 v[8:9], v[0:1], 2, v[56:57]
	v_mad_i64_i32 v[0:1], s[46:47], s6, v70, 0
	v_lshl_add_u64 v[10:11], v[0:1], 2, v[56:57]
	global_load_dwordx4 v[0:3], v[8:9], off nt
	global_load_dwordx4 v[4:7], v[10:11], off nt
	v_mad_i64_i32 v[8:9], s[46:47], s6, v72, 0
	v_lshl_add_u64 v[16:17], v[8:9], 2, v[56:57]
	v_mad_i64_i32 v[8:9], s[46:47], s6, v74, 0
	v_lshl_add_u64 v[18:19], v[8:9], 2, v[56:57]
	global_load_dwordx4 v[8:11], v[16:17], off nt
	global_load_dwordx4 v[12:15], v[18:19], off nt
	v_mad_i64_i32 v[16:17], s[46:47], s6, v76, 0
	v_lshl_add_u64 v[24:25], v[16:17], 2, v[56:57]
	v_mad_i64_i32 v[16:17], s[46:47], s6, v78, 0
	v_lshl_add_u64 v[26:27], v[16:17], 2, v[56:57]
	global_load_dwordx4 v[16:19], v[24:25], off nt
	global_load_dwordx4 v[20:23], v[26:27], off nt
	v_mad_i64_i32 v[24:25], s[46:47], s6, v80, 0
	v_lshl_add_u64 v[32:33], v[24:25], 2, v[56:57]
	v_mad_i64_i32 v[24:25], s[46:47], s6, v82, 0
	v_lshl_add_u64 v[34:35], v[24:25], 2, v[56:57]
	global_load_dwordx4 v[24:27], v[32:33], off nt
	global_load_dwordx4 v[28:31], v[34:35], off nt
	v_mad_i64_i32 v[32:33], s[46:47], s6, v84, 0
	v_lshl_add_u64 v[40:41], v[32:33], 2, v[56:57]
	v_mad_i64_i32 v[32:33], s[46:47], s6, v86, 0
	v_lshl_add_u64 v[42:43], v[32:33], 2, v[56:57]
	global_load_dwordx4 v[32:35], v[40:41], off nt
	global_load_dwordx4 v[36:39], v[42:43], off nt
	v_mad_i64_i32 v[40:41], s[46:47], s6, v88, 0
	v_lshl_add_u64 v[48:49], v[40:41], 2, v[56:57]
	v_mad_i64_i32 v[40:41], s[46:47], s6, v90, 0
	v_lshl_add_u64 v[50:51], v[40:41], 2, v[56:57]
	global_load_dwordx4 v[40:43], v[48:49], off nt
	global_load_dwordx4 v[44:47], v[50:51], off nt
	v_mad_i64_i32 v[48:49], s[46:47], s6, v92, 0
	v_lshl_add_u64 v[58:59], v[48:49], 2, v[56:57]
	v_mad_i64_i32 v[48:49], s[46:47], s6, v94, 0
	v_lshl_add_u64 v[60:61], v[48:49], 2, v[56:57]
	global_load_dwordx4 v[48:51], v[58:59], off nt
	global_load_dwordx4 v[52:55], v[60:61], off nt
	v_mad_i64_i32 v[58:59], s[46:47], s6, v96, 0
	v_lshl_add_u64 v[118:119], v[58:59], 2, v[56:57]
	v_mad_i64_i32 v[58:59], s[46:47], s6, v98, 0
	v_lshl_add_u64 v[120:121], v[58:59], 2, v[56:57]
	global_load_dwordx4 v[56:59], v[118:119], off nt
	global_load_dwordx4 v[60:63], v[120:121], off nt

; #define LAS __attribute__((address_space(3)))
; #define LDS_WAIT() asm volatile("s_waitcnt lgkmcnt(0)" ::: "memory")
; __device__ __forceinline__ void tr_to_lds(const f32x4 (&v)[16], LAS float* scr, int lane) {
;     const int r4 = lane >> 4, c4 = (lane & 15) * 4;
; #pragma unroll
;     for (int i = 0; i < 16; ++i) { LAS float* s = scr + (4 * i + r4) * 65 + c4; s[0] = v[i].x; s[1] = v[i].y; s[2] = v[i].z; s[3] = v[i].w; }
;     LDS_WAIT(); asm volatile("" ::: "memory");
; }
; __device__ __forceinline__ void convert_segments(const Args& args, unsigned char* ws, LAS unsigned char* lds, int seg_lo, int seg_hi, int part_lo, int part_hi, int nparts, int wid, int nw, int wave, int lane) {
;     ...
;         for (; it < it_hi; it += nw) {
;             const int kb = it / nblk, nb = it - kb * nblk;
;             const int drow = sg.ilv ? (256 * (nb >> 1) + 64 * (nb & 1) + sg.drow) : (sg.drow + 64 * nb);
;             tr_to_lds(v, scr, lane);
;             const int itn = it + nw;
;             if (itn < it_hi) { const int kbn = itn / nblk, nbn = itn - kbn * nblk; tr_load(W + (size_t)(64 * kbn) * sg.N + sg.scol + 64 * nbn, sg.N, v, lane); }
.LBB0_2126:
	v_add_u32_e32 v71, 0x410, v67
	s_waitcnt vmcnt(0)
	ds_write2_b32 v67, v0, v1 offset1:1
	ds_write2_b32 v67, v2, v3 offset0:2 offset1:3
	ds_write2_b32 v71, v4, v5 offset1:1
	v_add_u32_e32 v71, 0x418, v67
	ds_write2_b32 v71, v6, v7 offset1:1
	v_add_u32_e32 v71, 0x820, v67
	ds_write2_b32 v71, v8, v9 offset1:1
	v_add_u32_e32 v71, 0x828, v67
	ds_write2_b32 v71, v10, v11 offset1:1
	v_add_u32_e32 v71, 0xc30, v67
	ds_write2_b32 v71, v12, v13 offset1:1
	v_add_u32_e32 v71, 0xc38, v67
	ds_write2_b32 v71, v14, v15 offset1:1
	v_add_u32_e32 v71, 0x1040, v67
	ds_write2_b32 v71, v16, v17 offset1:1
	v_add_u32_e32 v71, 0x1048, v67
	ds_write2_b32 v71, v18, v19 offset1:1
	v_add_u32_e32 v71, 0x1450, v67
	ds_write2_b32 v71, v20, v21 offset1:1
	v_add_u32_e32 v71, 0x1458, v67
	ds_write2_b32 v71, v22, v23 offset1:1
	v_add_u32_e32 v71, 0x1860, v67
	ds_write2_b32 v71, v24, v25 offset1:1
	v_add_u32_e32 v71, 0x1868, v67
	ds_write2_b32 v71, v26, v27 offset1:1
	v_add_u32_e32 v71, 0x1c70, v67
	ds_write2_b32 v71, v28, v29 offset1:1
	v_add_u32_e32 v71, 0x1c78, v67
	ds_write2_b32 v71, v30, v31 offset1:1
	v_add_u32_e32 v71, 0x2080, v67
	ds_write2_b32 v71, v32, v33 offset1:1
	v_add_u32_e32 v71, 0x2088, v67
	ds_write2_b32 v71, v34, v35 offset1:1
	v_add_u32_e32 v71, 0x2490, v67
	ds_write2_b32 v71, v36, v37 offset1:1
	v_add_u32_e32 v71, 0x2498, v67
	ds_write2_b32 v71, v38, v39 offset1:1
	v_add_u32_e32 v71, 0x28a0, v67
	ds_write2_b32 v71, v40, v41 offset1:1
	v_add_u32_e32 v71, 0x28a8, v67
	ds_write2_b32 v71, v42, v43 offset1:1
	v_add_u32_e32 v71, 0x2cb0, v67
	ds_write2_b32 v71, v44, v45 offset1:1
	v_add_u32_e32 v71, 0x2cb8, v67
	ds_write2_b32 v71, v46, v47 offset1:1
	v_add_u32_e32 v71, 0x30c0, v67
	ds_write2_b32 v71, v48, v49 offset1:1
	v_add_u32_e32 v71, 0x30c8, v67
	ds_write2_b32 v71, v50, v51 offset1:1
	v_add_u32_e32 v71, 0x34d0, v67
	ds_write2_b32 v71, v52, v53 offset1:1
	v_add_u32_e32 v71, 0x34d8, v67
	ds_write2_b32 v71, v54, v55 offset1:1
	v_add_u32_e32 v71, 0x38e0, v67
	ds_write2_b32 v71, v56, v57 offset1:1
	v_add_u32_e32 v71, 0x38e8, v67
	ds_write2_b32 v71, v58, v59 offset1:1
	v_add_u32_e32 v71, 0x3cf0, v67
	ds_write2_b32 v71, v60, v61 offset1:1
	v_add_u32_e32 v71, 0x3cf8, v67
	ds_write2_b32 v71, v62, v63 offset1:1
	s_waitcnt lgkmcnt(0)
	s_add_i32 s46, s26, 0x3c0
	s_cmp_ge_i32 s46, s24
	s_cselect_b64 s[8:9], -1, 0
	s_and_b64 vcc, exec, s[8:9]
	s_cbranch_vccnz .LBB0_2128
	s_ashr_i32 s49, s46, 31
	s_add_i32 s26, s26, s49
	s_addk_i32 s26, 0x3c0
	s_xor_b32 s26, s26, s49
	s_xor_b32 s50, s49, s27
	s_mul_hi_u32 s49, s26, s39
	s_mul_i32 s51, s49, s15
	s_sub_i32 s26, s26, s51
	s_add_i32 s51, s49, 1
	s_sub_i32 s52, s26, s15
	s_cmp_ge_u32 s26, s15
	s_cselect_b32 s49, s51, s49
	s_cselect_b32 s26, s52, s26
	s_add_i32 s51, s49, 1
	s_cmp_ge_u32 s26, s15
	s_cselect_b32 s26, s51, s49
	s_xor_b32 s26, s26, s50
	s_sub_i32 s26, s26, s50
	s_lshl_b32 s49, s26, 6
	s_mul_hi_i32 s51, s49, s6
	s_mul_i32 s50, s49, s6
	s_lshl_b64 s[50:51], s[50:51], 2
	s_add_u32 s49, s12, s50
	s_mul_i32 s26, s41, s26
	s_addc_u32 s52, s14, s51
	s_add_i32 s26, s42, s26
	s_add_i32 s50, s26, 0xffffe000
	s_ashr_i32 s51, s50, 31
	s_lshl_b64 s[50:51], s[50:51], 2
	s_add_u32 s50, s49, s50
	s_addc_u32 s51, s52, s51
	v_mov_b32_e32 v117, v69
	v_lshl_add_u64 v[56:57], s[50:51], 0, v[116:117]
	v_lshl_add_u64 v[0:1], v[118:119], 2, v[56:57]
	v_lshl_add_u64 v[4:5], v[120:121], 2, v[56:57]
	v_lshl_add_u64 v[8:9], v[122:123], 2, v[56:57]
	v_lshl_add_u64 v[12:13], v[124:125], 2, v[56:57]
	v_lshl_add_u64 v[16:17], v[126:127], 2, v[56:57]
	v_lshl_add_u64 v[20:21], v[128:129], 2, v[56:57]
	v_lshl_add_u64 v[24:25], v[130:131], 2, v[56:57]
	v_lshl_add_u64 v[28:29], v[132:133], 2, v[56:57]
	v_lshl_add_u64 v[32:33], v[134:135], 2, v[56:57]
	v_lshl_add_u64 v[36:37], v[136:137], 2, v[56:57]
	v_lshl_add_u64 v[40:41], v[138:139], 2, v[56:57]
	v_lshl_add_u64 v[44:45], v[140:141], 2, v[56:57]
	v_lshl_add_u64 v[48:49], v[142:143], 2, v[56:57]
	v_lshl_add_u64 v[52:53], v[144:145], 2, v[56:57]
	v_lshl_add_u64 v[58:59], v[146:147], 2, v[56:57]
	v_lshl_add_u64 v[60:61], v[148:149], 2, v[56:57]
	global_load_dwordx4 v[0:3], v[0:1], off nt
	s_nop 0
	global_load_dwordx4 v[4:7], v[4:5], off nt
	s_nop 0
	global_load_dwordx4 v[8:11], v[8:9], off nt
	s_nop 0
	global_load_dwordx4 v[12:15], v[12:13], off nt
	s_nop 0
	global_load_dwordx4 v[16:19], v[16:17], off nt
	s_nop 0
	global_load_dwordx4 v[20:23], v[20:21], off nt
	s_nop 0
	global_load_dwordx4 v[24:27], v[24:25], off nt
	s_nop 0
	global_load_dwordx4 v[28:31], v[28:29], off nt
	s_nop 0
	global_load_dwordx4 v[32:35], v[32:33], off nt
	s_nop 0
	global_load_dwordx4 v[36:39], v[36:37], off nt
	s_nop 0
	global_load_dwordx4 v[40:43], v[40:41], off nt
	s_nop 0
	global_load_dwordx4 v[44:47], v[44:45], off nt
	s_nop 0
	global_load_dwordx4 v[48:51], v[48:49], off nt
	s_nop 0
	global_load_dwordx4 v[52:55], v[52:53], off nt
	s_nop 0
	global_load_dwordx4 v[56:59], v[58:59], off nt
	s_nop 0
	global_load_dwordx4 v[60:63], v[60:61], off nt
